# state items: next round gathers and V^T loads prefetched after the MFMAs
# baseline (speedup 1.0000x reference)
.LBB0_569:
	s_add_u32 s46, s62, 0x1200100
	s_addc_u32 s47, s63, 0
	s_sub_i32 s2, s33, s82
	s_addk_i32 s2, 0x80
	v_bfe_u32 v189, v0, 5, 1
	s_cmpk_gt_u32 s2, 0x7f
	v_lshrrev_b32_e32 v188, 6, v0
	v_and_b32_e32 v156, 31, v0
	v_lshrrev_b32_e32 v124, 4, v0
	v_lshlrev_b32_e32 v122, 4, v189
	v_lshlrev_b32_e32 v123, 13, v189
	s_cbranch_scc1 .LBB0_577
	v_lshl_or_b32 v1, v188, 5, v156
	s_movk_i32 s0, 0x110
	v_lshlrev_b32_e32 v2, 4, v0
	s_mov_b32 s1, 0
	v_mad_u32_u24 v1, v1, s0, 0
	v_and_b32_e32 v2, 0xf0, v2
	s_lshr_b32 s0, s2, 1
	v_add_u32_e32 v4, 0, v2
	s_and_b32 s3, s2, 1
	s_lshl_b64 s[6:7], s[0:1], 15
	v_and_b32_e32 v2, 15, v0
	v_lshlrev_b32_e32 v6, 7, v124
	s_lshl_b64 s[8:9], s[0:1], 20
	s_lshl_b32 s10, s3, 5
	v_lshlrev_b32_e32 v3, 3, v2
	v_lshl_or_b32 v6, s3, 12, v6
	v_lshl_or_b32 v36, v2, 4, s6
	v_lshlrev_b32_e32 v2, 6, v188
	v_or3_b32 v34, s8, v3, v6
	v_or3_b32 v2, v2, s10, v156
	v_lshrrev_b32_e32 v3, 1, v0
	s_lshl_b64 s[4:5], s[0:1], 19
	v_lshlrev_b32_e32 v2, 6, v2
	v_and_b32_e32 v3, 16, v3
	s_lshl_b32 s11, s2, 18
	v_or3_b32 v38, s4, v2, v3
	v_lshlrev_b32_e32 v2, 9, v0
	v_mov_b32_e32 v3, 0x1c38000
	s_lshl_b32 s2, s2, 6
	v_bitop3_b32 v2, s11, v3, v2 bitop3:0xc8
	s_and_b32 s2, s2, 0x380
	v_or_b32_e32 v2, s2, v2
	v_lshlrev_b32_e32 v3, 1, v156
	v_or3_b32 v2, v123, v3, v2
	v_or_b32_e32 v64, 0x5c40, v2
	v_mov_b32_e32 v65, 0
	s_mov_b64 s[2:3], 0x15800400
	v_mov_b32_e32 v39, s5
	v_lshl_add_u64 v[40:41], v[64:65], 0, s[2:3]
	v_or_b32_e32 v64, 64, v2
	s_mov_b64 s[4:5], 0x15800c00
	v_lshl_add_u64 v[42:43], v[64:65], 0, s[4:5]
	v_or_b32_e32 v64, 0x5840, v2
	v_lshl_add_u64 v[44:45], v[64:65], 0, s[2:3]
	v_or_b32_e32 v64, 0x5440, v2
	v_lshl_add_u64 v[46:47], v[64:65], 0, s[2:3]
	v_or_b32_e32 v64, 0x5040, v2
	v_lshl_add_u64 v[48:49], v[64:65], 0, s[2:3]
	v_or_b32_e32 v64, 0x4c40, v2
	v_lshl_add_u64 v[52:53], v[64:65], 0, s[2:3]
	v_or_b32_e32 v64, 0x4840, v2
	v_lshl_add_u64 v[54:55], v[64:65], 0, s[2:3]
	v_or_b32_e32 v64, 0x1000, v2
	v_lshl_add_u64 v[56:57], v[64:65], 0, s[2:3]
	v_or_b32_e32 v64, 0x1400, v2
	v_lshl_add_u64 v[58:59], v[64:65], 0, s[2:3]
	v_or_b32_e32 v64, 0x1800, v2
	v_lshl_add_u64 v[60:61], v[64:65], 0, s[2:3]
	v_or_b32_e32 v64, 0x1c00, v2
	v_lshl_add_u64 v[62:63], v[64:65], 0, s[2:3]
	v_or_b32_e32 v64, 0x4000, v2
	v_lshl_add_u64 v[66:67], v[64:65], 0, s[2:3]
	v_or_b32_e32 v64, 0x4400, v2
	v_lshl_add_u64 v[68:69], v[64:65], 0, s[2:3]
	v_or_b32_e32 v64, 0x4800, v2
	v_lshl_add_u64 v[70:71], v[64:65], 0, s[2:3]
	v_or_b32_e32 v64, 0x4c00, v2
	v_lshl_add_u64 v[72:73], v[64:65], 0, s[2:3]
	v_or_b32_e32 v64, 0x5000, v2
	v_lshl_add_u64 v[74:75], v[64:65], 0, s[2:3]
	v_or_b32_e32 v64, 0x5400, v2
	v_lshl_add_u64 v[76:77], v[64:65], 0, s[2:3]
	v_or_b32_e32 v64, 0x5800, v2
	v_lshl_add_u64 v[78:79], v[64:65], 0, s[2:3]
	v_or_b32_e32 v64, 0x5c00, v2
	v_lshl_add_u64 v[80:81], v[64:65], 0, s[2:3]
	v_or_b32_e32 v64, 0x1040, v2
	v_lshl_add_u64 v[82:83], v[64:65], 0, s[2:3]
	v_or_b32_e32 v64, 0x1440, v2
	v_lshl_add_u64 v[84:85], v[64:65], 0, s[2:3]
	v_or_b32_e32 v64, 0x1840, v2
	v_lshl_add_u64 v[86:87], v[64:65], 0, s[2:3]
	v_or_b32_e32 v64, 0x1c40, v2
	v_lshl_add_u64 v[88:89], v[64:65], 0, s[2:3]
	v_or_b32_e32 v64, 0x4040, v2
	v_mul_u32_u24_e32 v5, 0x110, v124
	v_mov_b32_e32 v3, v65
	v_lshl_add_u64 v[90:91], v[64:65], 0, s[2:3]
	v_or_b32_e32 v64, 0x4440, v2
	v_mov_b32_e32 v35, s9
	v_mov_b32_e32 v37, s7
	s_mov_b32 s10, 16
	v_lshl_add_u64 v[50:51], v[2:3], 0, s[4:5]
	v_lshl_add_u64 v[92:93], v[64:65], 0, s[2:3]
	s_mov_b32 s11, 0x17800000
	s_mov_b32 s12, 0x1200000
	s_mov_b32 s13, 0x5040100
	v_add_u32_e32 v1, v1, v122
	v_add_u32_e32 v125, v4, v5
	s_mov_b32 s14, 0xd800000
	s_mov_b32 s15, 0xd802000
	s_mov_b32 s16, 0xd804000
	s_mov_b32 s17, 0xd806000
	s_mov_b32 s18, 0xd808000
	s_mov_b32 s19, 0xd80a000
	s_mov_b32 s20, 0xd80c000
	s_mov_b32 s21, 0xd80e000
	s_mov_b64 s[2:3], 0x10000
	s_mov_b64 s[4:5], 0x800
	s_mov_b64 s[6:7], 0x8000
	s_mov_b64 s[8:9], 0x40000
	v_mov_b32_e32 v64, v65
	v_mov_b32_e32 v94, v65
	v_mov_b32_e32 v95, v65
	v_lshl_add_u64 v[190:191], s[62:63], 0, v[50:51]
	v_lshl_add_u64 v[192:193], s[62:63], 0, v[56:57]
	v_lshl_add_u64 v[194:195], s[62:63], 0, v[60:61]
	v_lshl_add_u64 v[196:197], s[62:63], 0, v[62:63]
	v_lshl_add_u64 v[198:199], s[62:63], 0, v[80:81]
	v_lshl_add_u64 v[200:201], s[62:63], 0, v[58:59]
	v_lshl_add_u64 v[202:203], s[62:63], 0, v[66:67]
	v_lshl_add_u64 v[204:205], s[62:63], 0, v[68:69]
	v_lshl_add_u64 v[206:207], s[62:63], 0, v[70:71]
	v_lshl_add_u64 v[208:209], s[62:63], 0, v[72:73]
	v_lshl_add_u64 v[210:211], s[62:63], 0, v[74:75]
	v_lshl_add_u64 v[212:213], s[62:63], 0, v[76:77]
	v_lshl_add_u64 v[214:215], s[62:63], 0, v[78:79]
	v_lshl_add_u64 v[216:217], s[62:63], 0, v[42:43]
	v_lshl_add_u64 v[218:219], s[62:63], 0, v[82:83]
	v_lshl_add_u64 v[220:221], s[62:63], 0, v[84:85]
	v_lshl_add_u64 v[222:223], s[62:63], 0, v[86:87]
	v_lshl_add_u64 v[224:225], s[62:63], 0, v[88:89]
	v_lshl_add_u64 v[226:227], s[62:63], 0, v[90:91]
	v_lshl_add_u64 v[228:229], s[62:63], 0, v[92:93]
	v_lshl_add_u64 v[230:231], s[62:63], 0, v[54:55]
	v_lshl_add_u64 v[232:233], s[62:63], 0, v[52:53]
	v_lshl_add_u64 v[234:235], s[62:63], 0, v[48:49]
	v_lshl_add_u64 v[236:237], s[62:63], 0, v[46:47]
	v_lshl_add_u64 v[238:239], s[62:63], 0, v[44:45]
	v_lshl_add_u64 v[240:241], s[62:63], 0, v[40:41]
	v_lshl_add_u64 v[242:243], s[62:63], 0, v[38:39]
	v_add_co_u32_e32 v244, vcc, s11, v242
	s_nop 1
	v_addc_co_u32_e32 v245, vcc, 0, v243, vcc
	global_load_ushort v138, v[196:197], off
	global_load_ushort v142, v[202:203], off
	global_load_ushort v143, v[204:205], off
	global_load_ushort v139, v[206:207], off
	global_load_ushort v157, v[208:209], off
	global_load_ushort v140, v[210:211], off
	global_load_ushort v162, v[212:213], off
	global_load_ushort v141, v[214:215], off
	global_load_ushort v163, v[190:191], off offset:-2048
	global_load_ushort v164, v[190:191], off offset:-1024
	global_load_ushort v165, v[190:191], off
	global_load_ushort v166, v[190:191], off offset:1024
	global_load_ushort v167, v[192:193], off
	global_load_ushort v181, v[200:201], off
	global_load_ushort v182, v[194:195], off
	global_load_ushort v168, v[190:191], off offset:-1984
	global_load_ushort v169, v[198:199], off
	global_load_ushort v170, v[216:217], off offset:-1024
	global_load_ushort v171, v[216:217], off
	global_load_ushort v185, v[216:217], off offset:1024
	global_load_ushort v186, v[218:219], off
	global_load_ushort v172, v[220:221], off
	global_load_ushort v183, v[222:223], off
	global_load_ushort v184, v[224:225], off
	global_load_ushort v173, v[226:227], off
	global_load_ushort v174, v[228:229], off
	global_load_ushort v175, v[230:231], off
	global_load_ushort v176, v[232:233], off
	global_load_ushort v177, v[234:235], off
	global_load_ushort v178, v[236:237], off
	global_load_ushort v179, v[238:239], off
	global_load_ushort v180, v[240:241], off
	global_load_dwordx4 v[246:249], v[244:245], off offset:1024
	global_load_dwordx4 v[250:253], v[244:245], off offset:1056
.LBB0_571:
	v_lshl_add_u64 v[102:103], s[62:63], 0, v[36:37]
	s_nop 0
	v_add_co_u32_e32 v4, vcc, s12, v102
	v_lshl_add_u64 v[126:127], s[62:63], 0, v[34:35]
	s_nop 0
	s_nop 1
	v_addc_co_u32_e32 v5, vcc, 0, v103, vcc
	v_add_co_u32_e32 v144, vcc, s14, v126
	v_cvt_pk_bf16_f32 v120, v64, v65
	s_nop 0
	s_nop 1
	v_addc_co_u32_e32 v145, vcc, 0, v127, vcc
	v_add_co_u32_e32 v146, vcc, s15, v126
	v_cvt_pk_bf16_f32 v121, v94, v95
	s_nop 0
	s_nop 1
	v_addc_co_u32_e32 v147, vcc, 0, v127, vcc
	v_add_co_u32_e32 v148, vcc, s16, v126
	s_add_i32 s10, s10, -1
	s_nop 0
	s_nop 1
	v_addc_co_u32_e32 v149, vcc, 0, v127, vcc
	v_add_co_u32_e32 v150, vcc, s17, v126
	v_lshl_add_u64 v[34:35], v[34:35], 0, s[2:3]
	s_nop 0
	s_nop 1
	v_addc_co_u32_e32 v151, vcc, 0, v127, vcc
	v_add_co_u32_e32 v152, vcc, s18, v126
	s_nop 1
	v_addc_co_u32_e32 v153, vcc, 0, v127, vcc
	v_add_co_u32_e32 v154, vcc, s19, v126
	s_nop 0
	s_nop 1
	v_addc_co_u32_e32 v155, vcc, 0, v127, vcc
	v_add_co_u32_e32 v158, vcc, s20, v126
	v_lshl_add_u64 v[36:37], v[36:37], 0, s[4:5]
	s_nop 0
	s_nop 1
	v_addc_co_u32_e32 v159, vcc, 0, v127, vcc
	v_add_co_u32_e32 v160, vcc, s21, v126
	s_nop 0
	s_nop 1
	v_addc_co_u32_e32 v161, vcc, 0, v127, vcc
	global_load_dwordx4 v[100:103], v[4:5], off offset:1024
	global_load_dwordx4 v[104:107], v[4:5], off offset:1280
	global_load_dwordx4 v[108:111], v[4:5], off offset:1536
	global_load_dwordx4 v[112:115], v[4:5], off offset:1792
	global_load_dwordx4 v[116:119], v[4:5], off offset:2048
	global_load_dwordx4 v[126:129], v[4:5], off offset:2304
	global_load_dwordx4 v[130:133], v[4:5], off offset:2560
	global_load_dwordx4 v[134:137], v[4:5], off offset:2816
	s_cmp_eq_u32 s10, 15
	s_cbranch_scc1 .Lst_first
	s_waitcnt vmcnt(16)
	s_branch .Lst_go
.Lst_first:
	s_waitcnt vmcnt(8)
.Lst_go:
	v_perm_b32 v139, v157, v139, s13
	v_perm_b32 v140, v162, v140, s13
	v_perm_b32 v5, v138, v182, s13
	v_perm_b32 v4, v181, v167, s13
	v_perm_b32 v3, v166, v165, s13
	v_perm_b32 v2, v164, v163, s13
	v_perm_b32 v141, v169, v141, s13
	v_perm_b32 v138, v143, v142, s13
	v_perm_b32 v24, v172, v186, s13
	v_perm_b32 v23, v185, v171, s13
	v_perm_b32 v22, v170, v168, s13
	s_waitcnt lgkmcnt(0)
	s_barrier
	v_perm_b32 v25, v184, v183, s13
	s_nop 1
	v_mfma_f32_32x32x16_bf16 v[2:17], v[2:5], v[246:249], 0
	v_perm_b32 v143, v180, v179, s13
	v_perm_b32 v142, v178, v177, s13
	s_nop 1
	v_mfma_f32_32x32x16_bf16 v[18:33], v[22:25], v[246:249], 0
	s_nop 1
	v_mfma_f32_32x32x16_bf16 v[2:17], v[138:141], v[250:253], v[2:17]
	v_perm_b32 v141, v176, v175, s13
	v_perm_b32 v140, v174, v173, s13
	s_nop 1
	v_mfma_f32_32x32x16_bf16 v[18:33], v[140:143], v[250:253], v[18:33]
	v_lshl_add_u64 v[40:41], v[40:41], 0, s[8:9]
	v_lshl_add_u64 v[42:43], v[42:43], 0, s[8:9]
	v_lshl_add_u64 v[44:45], v[44:45], 0, s[8:9]
	v_lshl_add_u64 v[46:47], v[46:47], 0, s[8:9]
	v_lshl_add_u64 v[48:49], v[48:49], 0, s[8:9]
	v_lshl_add_u64 v[50:51], v[50:51], 0, s[8:9]
	v_lshl_add_u64 v[52:53], v[52:53], 0, s[8:9]
	v_lshl_add_u64 v[54:55], v[54:55], 0, s[8:9]
	v_lshl_add_u64 v[56:57], v[56:57], 0, s[8:9]
	v_lshl_add_u64 v[58:59], v[58:59], 0, s[8:9]
	v_lshl_add_u64 v[60:61], v[60:61], 0, s[8:9]
	v_lshl_add_u64 v[62:63], v[62:63], 0, s[8:9]
	v_lshl_add_u64 v[66:67], v[66:67], 0, s[8:9]
	v_lshl_add_u64 v[68:69], v[68:69], 0, s[8:9]
	v_lshl_add_u64 v[70:71], v[70:71], 0, s[8:9]
	v_lshl_add_u64 v[72:73], v[72:73], 0, s[8:9]
	v_lshl_add_u64 v[74:75], v[74:75], 0, s[8:9]
	v_lshl_add_u64 v[76:77], v[76:77], 0, s[8:9]
	v_lshl_add_u64 v[78:79], v[78:79], 0, s[8:9]
	v_lshl_add_u64 v[80:81], v[80:81], 0, s[8:9]
	v_lshl_add_u64 v[82:83], v[82:83], 0, s[8:9]
	v_lshl_add_u64 v[84:85], v[84:85], 0, s[8:9]
	v_lshl_add_u64 v[86:87], v[86:87], 0, s[8:9]
	v_lshl_add_u64 v[88:89], v[88:89], 0, s[8:9]
	v_lshl_add_u64 v[90:91], v[90:91], 0, s[8:9]
	v_lshl_add_u64 v[92:93], v[92:93], 0, s[8:9]
	v_lshl_add_u64 v[38:39], v[38:39], 0, s[6:7]
	v_lshl_add_u64 v[190:191], s[62:63], 0, v[50:51]
	v_lshl_add_u64 v[192:193], s[62:63], 0, v[56:57]
	v_lshl_add_u64 v[194:195], s[62:63], 0, v[60:61]
	v_lshl_add_u64 v[196:197], s[62:63], 0, v[62:63]
	v_lshl_add_u64 v[198:199], s[62:63], 0, v[80:81]
	v_lshl_add_u64 v[200:201], s[62:63], 0, v[58:59]
	v_lshl_add_u64 v[202:203], s[62:63], 0, v[66:67]
	v_lshl_add_u64 v[204:205], s[62:63], 0, v[68:69]
	v_lshl_add_u64 v[206:207], s[62:63], 0, v[70:71]
	v_lshl_add_u64 v[208:209], s[62:63], 0, v[72:73]
	v_lshl_add_u64 v[210:211], s[62:63], 0, v[74:75]
	v_lshl_add_u64 v[212:213], s[62:63], 0, v[76:77]
	v_lshl_add_u64 v[214:215], s[62:63], 0, v[78:79]
	v_lshl_add_u64 v[216:217], s[62:63], 0, v[42:43]
	v_lshl_add_u64 v[218:219], s[62:63], 0, v[82:83]
	v_lshl_add_u64 v[220:221], s[62:63], 0, v[84:85]
	v_lshl_add_u64 v[222:223], s[62:63], 0, v[86:87]
	v_lshl_add_u64 v[224:225], s[62:63], 0, v[88:89]
	v_lshl_add_u64 v[226:227], s[62:63], 0, v[90:91]
	v_lshl_add_u64 v[228:229], s[62:63], 0, v[92:93]
	v_lshl_add_u64 v[230:231], s[62:63], 0, v[54:55]
	v_lshl_add_u64 v[232:233], s[62:63], 0, v[52:53]
	v_lshl_add_u64 v[234:235], s[62:63], 0, v[48:49]
	v_lshl_add_u64 v[236:237], s[62:63], 0, v[46:47]
	v_lshl_add_u64 v[238:239], s[62:63], 0, v[44:45]
	v_lshl_add_u64 v[240:241], s[62:63], 0, v[40:41]
	v_lshl_add_u64 v[242:243], s[62:63], 0, v[38:39]
	v_add_co_u32_e32 v244, vcc, s11, v242
	s_nop 1
	v_addc_co_u32_e32 v245, vcc, 0, v243, vcc
	global_load_ushort v138, v[196:197], off
	global_load_ushort v142, v[202:203], off
	global_load_ushort v143, v[204:205], off
	global_load_ushort v139, v[206:207], off
	global_load_ushort v157, v[208:209], off
	global_load_ushort v140, v[210:211], off
	global_load_ushort v162, v[212:213], off
	global_load_ushort v141, v[214:215], off
	global_load_ushort v163, v[190:191], off offset:-2048
	global_load_ushort v164, v[190:191], off offset:-1024
	global_load_ushort v165, v[190:191], off
	global_load_ushort v166, v[190:191], off offset:1024
	global_load_ushort v167, v[192:193], off
	global_load_ushort v181, v[200:201], off
	global_load_ushort v182, v[194:195], off
	global_load_ushort v168, v[190:191], off offset:-1984
	global_load_ushort v169, v[198:199], off
	global_load_ushort v170, v[216:217], off offset:-1024
	global_load_ushort v171, v[216:217], off
	global_load_ushort v185, v[216:217], off offset:1024
	global_load_ushort v186, v[218:219], off
	global_load_ushort v172, v[220:221], off
	global_load_ushort v183, v[222:223], off
	global_load_ushort v184, v[224:225], off
	global_load_ushort v173, v[226:227], off
	global_load_ushort v174, v[228:229], off
	global_load_ushort v175, v[230:231], off
	global_load_ushort v176, v[232:233], off
	global_load_ushort v177, v[234:235], off
	global_load_ushort v178, v[236:237], off
	global_load_ushort v179, v[238:239], off
	global_load_ushort v180, v[240:241], off
	global_load_dwordx4 v[246:249], v[244:245], off offset:1024
	global_load_dwordx4 v[250:253], v[244:245], off offset:1056
	s_nop 3
	ds_write_b128 v1, v[2:5]
	ds_write_b128 v1, v[6:9] offset:32
	ds_write_b128 v1, v[10:13] offset:64
	ds_write_b128 v1, v[14:17] offset:96
	s_nop 3
	ds_write_b128 v1, v[18:21] offset:128
	ds_write_b128 v1, v[22:25] offset:160
	ds_write_b128 v1, v[26:29] offset:192
	ds_write_b128 v1, v[30:33] offset:224
	s_waitcnt lgkmcnt(0)
	s_barrier
	global_store_dwordx2 v[144:145], v[120:121], off offset:1024
	ds_read_b128 v[2:5], v125
	ds_read_b128 v[6:9], v125 offset:8704
	ds_read_b128 v[10:13], v125 offset:17408
	ds_read_b128 v[14:17], v125 offset:26112
	ds_read_b128 v[18:21], v125 offset:34816
	ds_read_b128 v[22:25], v125 offset:43520
	ds_read_b128 v[26:29], v125 offset:52224
	ds_read_b128 v[30:33], v125 offset:60928
	s_waitcnt lgkmcnt(7)
	v_pk_add_f32 v[2:3], v[64:65], v[2:3]
	v_pk_add_f32 v[4:5], v[94:95], v[4:5]
	s_waitcnt vmcnt(42)
	v_pk_mul_f32 v[94:95], v[100:101], v[2:3]
	v_pk_mul_f32 v[64:65], v[102:103], v[4:5]
	s_waitcnt lgkmcnt(6)
	v_pk_fma_f32 v[2:3], v[100:101], v[2:3], v[6:7]
	v_pk_fma_f32 v[4:5], v[102:103], v[4:5], v[8:9]
	v_cvt_pk_bf16_f32 v6, v94, v95
	v_cvt_pk_bf16_f32 v7, v64, v65
	s_waitcnt vmcnt(41)
	v_pk_mul_f32 v[8:9], v[106:107], v[4:5]
	v_pk_mul_f32 v[64:65], v[104:105], v[2:3]
	s_waitcnt lgkmcnt(5)
	v_pk_fma_f32 v[4:5], v[106:107], v[4:5], v[12:13]
	v_pk_fma_f32 v[2:3], v[104:105], v[2:3], v[10:11]
	global_store_dwordx2 v[146:147], v[6:7], off offset:1024
	v_cvt_pk_bf16_f32 v6, v64, v65
	v_cvt_pk_bf16_f32 v7, v8, v9
	s_waitcnt vmcnt(41)
	v_pk_mul_f32 v[8:9], v[110:111], v[4:5]
	v_pk_mul_f32 v[10:11], v[108:109], v[2:3]
	s_waitcnt lgkmcnt(4)
	v_pk_fma_f32 v[4:5], v[110:111], v[4:5], v[16:17]
	v_pk_fma_f32 v[2:3], v[108:109], v[2:3], v[14:15]
	global_store_dwordx2 v[148:149], v[6:7], off offset:1024
	v_cvt_pk_bf16_f32 v6, v10, v11
	v_cvt_pk_bf16_f32 v7, v8, v9
	s_waitcnt vmcnt(41)
	v_pk_mul_f32 v[8:9], v[114:115], v[4:5]
	v_pk_mul_f32 v[10:11], v[112:113], v[2:3]
	s_waitcnt lgkmcnt(3)
	v_pk_fma_f32 v[4:5], v[114:115], v[4:5], v[20:21]
	v_pk_fma_f32 v[2:3], v[112:113], v[2:3], v[18:19]
	global_store_dwordx2 v[150:151], v[6:7], off offset:1024
	v_cvt_pk_bf16_f32 v6, v10, v11
	v_cvt_pk_bf16_f32 v7, v8, v9
	s_waitcnt vmcnt(41)
	v_pk_mul_f32 v[8:9], v[118:119], v[4:5]
	v_pk_mul_f32 v[10:11], v[116:117], v[2:3]
	s_waitcnt lgkmcnt(2)
	v_pk_fma_f32 v[4:5], v[118:119], v[4:5], v[24:25]
	v_pk_fma_f32 v[2:3], v[116:117], v[2:3], v[22:23]
	global_store_dwordx2 v[152:153], v[6:7], off offset:1024
	v_cvt_pk_bf16_f32 v6, v10, v11
	v_cvt_pk_bf16_f32 v7, v8, v9
	s_waitcnt vmcnt(41)
	v_pk_mul_f32 v[8:9], v[128:129], v[4:5]
	v_pk_mul_f32 v[10:11], v[126:127], v[2:3]
	s_waitcnt lgkmcnt(1)
	v_pk_fma_f32 v[4:5], v[128:129], v[4:5], v[28:29]
	v_pk_fma_f32 v[2:3], v[126:127], v[2:3], v[26:27]
	global_store_dwordx2 v[154:155], v[6:7], off offset:1024
	v_cvt_pk_bf16_f32 v6, v10, v11
	v_cvt_pk_bf16_f32 v7, v8, v9
	s_waitcnt vmcnt(41)
	v_pk_mul_f32 v[8:9], v[132:133], v[4:5]
	v_pk_mul_f32 v[10:11], v[130:131], v[2:3]
	s_waitcnt lgkmcnt(0)
	v_pk_fma_f32 v[4:5], v[132:133], v[4:5], v[32:33]
	v_pk_fma_f32 v[2:3], v[130:131], v[2:3], v[30:31]
	s_cmp_eq_u32 s10, 0
	global_store_dwordx2 v[158:159], v[6:7], off offset:1024
	v_cvt_pk_bf16_f32 v6, v10, v11
	v_cvt_pk_bf16_f32 v7, v8, v9
	s_waitcnt vmcnt(41)
	v_pk_mul_f32 v[94:95], v[136:137], v[4:5]
	v_pk_mul_f32 v[64:65], v[134:135], v[2:3]
	global_store_dwordx2 v[160:161], v[6:7], off offset:1024
	s_cbranch_scc0 .LBB0_571
	s_waitcnt vmcnt(0)
	s_barrier
	s_and_saveexec_b64 s[2:3], s[44:45]
	s_cbranch_execz .LBB0_576
	s_mov_b64 s[4:5], exec
	buffer_wbl2 sc1
	s_waitcnt vmcnt(0)
	s_waitcnt vmcnt(0)
	v_mbcnt_lo_u32_b32 v1, s4, 0
	v_mbcnt_hi_u32_b32 v1, s5, v1
	v_cmp_eq_u32_e32 vcc, 0, v1
	s_and_saveexec_b64 s[6:7], vcc
	s_cbranch_execz .LBB0_575
	s_lshl_b64 s[0:1], s[0:1], 2
	s_add_u32 s0, s46, s0
	s_addc_u32 s1, s47, s1
	s_bcnt1_i32_b64 s4, s[4:5]
	v_mov_b32_e32 v1, 0
	v_mov_b32_e32 v2, s4
	global_atomic_add v1, v2, s[0:1]
	global_atomic_add v1, v2, s[46:47] offset:256
